# attention loop: one static s_setprio 1 for waves 4-7 (younger half), reset after the loop
# speedup vs baseline: 1.0306x; 1.0024x over previous
; DEV int ltid() { int t = threadIdx.x; asm volatile("" : "+v"(t)); return t; }
; DEV void attn_tile(const Params& p, int l, int tile, char* smem, bool do_store = true) {
;     ...
;   if (tile < 1024) { b = tile >> 7; head = (tile >> 5) & 3; q0 = (tile & 31) * 128; nkeys = TK; qbase = b * SEQ; }
;   else { const int tt = tile - 1024; b = tt >> 3; head = (tt >> 1) & 3; q0 = (tt & 1) * 128; nkeys = CTXL; qbase = T_LAT + b * CTXL; }
;   const int tid = ltid(), lane = tid & 63, w = tid >> 6, ql = lane & 31, hh = lane >> 5, map = w >> 2, qg = w & 3;
;   const int qrow = qbase + q0 + qg * 32 + ql;
;   const float lam_init = l == 0 ? 0.2f : 0.35550907f;
;   float lam;
;   {
;     const float a1 = p.att_lq1[l * 64 + lane] * p.att_lk1[l * 64 + lane];
;     const float a2 = p.att_lq2[l * 64 + lane] * p.att_lk2[l * 64 + lane];
;     lam = __expf(wsum(a1)) - __expf(wsum(a2)) + lam_init;
;   }
;   bf16x8 qf[4];
; #pragma unroll
;   for (int s = 0; s < 4; ++s) qf[s] = *(const bf16x8*)(ZQ + (size_t)qrow * 512 + head * 128 + map * 64 + s * 16 + hh * 8);
;   f32x16 o[4];
; #pragma unroll
;   for (int dt = 0; dt < 4; ++dt)
; #pragma unroll
;     for (int e = 0; e < 16; ++e) o[dt][e] = 0.f;
;   float m = -1e30f, lsum = 0.f;
;   const int kr0 = tid >> 4, kch = tid & 15;
;   const int vr0 = tid >> 4, vch = tid & 15;
;   const bf16_t* vtb = VT + ((size_t)((b * 4 + head) * 128)) * TK;
;   u32x4 kreg[4], vreg[4];
;   auto gload = [&](int kt) {
;     const int k0 = kt * 128;
; #pragma unroll
;     for (int i = 0; i < 4; ++i) {
;       const int kidx = k0 + kr0 + 32 * i;
;       const int krow = kidx < CTXL ? T_LAT + b * CTXL + kidx : b * SEQ + kidx - CTXL;
;       kreg[i] = *(const u32x4*)(ZK + (size_t)krow * 512 + head * 128 + kch * 8);
;       vreg[i] = *(const u32x4*)(vtb + (size_t)(vr0 + 32 * i) * TK + k0 + vch * 8);
;     }
;   };
;   auto lstore = [&](int st) {
;     char* Ks = smem + st * ATT2_ST;
;     char* Vs = Ks + 128 * KROW;
; #pragma unroll
;     for (int i = 0; i < 4; ++i) {
;       *(u32x4*)(Ks + (kr0 + 32 * i) * KROW + kch * 16) = kreg[i];
;       *(u32x4*)(Vs + (vr0 + 32 * i) * KROW + vch * 16) = vreg[i];
;     }
;   };
;   const int nkt = nkeys >> 7;
;   gload(0);
.LBB0_598:
	v_mov_b32_e32 v192, v226
	v_readlane_b32 s56, v254, 58
	v_readlane_b32 s57, v254, 59
	v_and_or_b32 v2, v192, 63, s96
	v_readlane_b32 s58, v254, 60
	v_readlane_b32 s59, v254, 61
	v_readlane_b32 s60, v254, 62
	v_readlane_b32 s61, v254, 63
	v_readlane_b32 s62, v255, 0
	v_readlane_b32 s63, v255, 1
	v_readlane_b32 s64, v255, 2
	v_readlane_b32 s65, v255, 3
	v_readlane_b32 s66, v255, 4
	v_readlane_b32 s67, v255, 5
	v_ashrrev_i32_e32 v3, 31, v2
	v_readlane_b32 s68, v255, 6
	v_readlane_b32 s69, v255, 7
	v_readlane_b32 s70, v255, 8
	v_readlane_b32 s71, v255, 9
	s_mov_b64 s[56:57], s[60:61]
	v_lshlrev_b64 v[2:3], 2, v[2:3]
	s_mov_b64 s[58:59], s[62:63]
	s_mov_b64 s[60:61], s[64:65]
	s_mov_b64 s[62:63], s[66:67]
	s_mov_b64 s[64:65], s[68:69]
	s_mov_b64 s[66:67], s[70:71]
	v_lshl_add_u64 v[4:5], s[64:65], 0, v[2:3]
	global_load_dword v1, v[4:5], off
	v_lshl_add_u64 v[4:5], s[66:67], 0, v[2:3]
	global_load_dword v6, v[4:5], off
	v_readlane_b32 s56, v251, 21
	v_readlane_b32 s57, v251, 22
	v_readlane_b32 s58, v251, 23
	v_readlane_b32 s59, v251, 24
	v_lshl_add_u64 v[4:5], s[56:57], 0, v[2:3]
	global_load_dword v4, v[4:5], off
	v_lshl_add_u64 v[2:3], s[58:59], 0, v[2:3]
	global_load_dword v2, v[2:3], off
	v_bfe_u32 v193, v192, 6, 2
	v_and_b32_e32 v194, 31, v192
	s_add_i32 s0, s38, s39
	v_lshlrev_b32_e32 v0, 5, v193
	v_add3_u32 v0, s0, v194, v0
	v_readlane_b32 s0, v252, 19
	v_readlane_b32 s1, v252, 20
	v_ashrrev_i32_e32 v195, 8, v192
	v_bfe_u32 v190, v192, 5, 1
	v_lshlrev_b32_e32 v96, 4, v190
	v_ashrrev_i32_e32 v200, 4, v192
	v_readlane_b32 s64, v251, 29
	v_readlane_b32 s65, v251, 30
	v_readlane_b32 s64, v255, 38
	v_readlane_b32 s52, v252, 21
	v_add_u32_e32 v14, 32, v200
	v_readlane_b32 s65, v255, 39
	v_readlane_b32 s53, v252, 22
	v_add_u32_e32 v22, 64, v200
	s_movk_i32 s41, 0x2200
	v_add_u32_e32 v32, 0x60, v200
	v_readlane_b32 s60, v251, 25
	v_readlane_b32 s61, v251, 26
	v_readlane_b32 s66, v251, 31
	v_readlane_b32 s67, v251, 32
	v_readlane_b32 s68, v251, 33
	v_readlane_b32 s69, v251, 34
	v_readlane_b32 s70, v251, 35
	v_readlane_b32 s71, v251, 36
	v_readlane_b32 s60, v255, 32
	v_readlane_b32 s66, v255, 34
	v_readlane_b32 s68, v255, 36
	v_lshrrev_b32_e32 v191, 6, v192
	v_lshl_or_b32 v204, v195, 7, v96
	v_mul_u32_u24_e32 v201, 0x110, v194
	v_mov_b32_e32 v209, 0
	v_mov_b32_e32 v208, 0xf149f2ca
	v_readlane_b32 s61, v255, 33
	v_readlane_b32 s67, v255, 35
	v_readlane_b32 s69, v255, 37
	v_readlane_b32 s70, v255, 41
	s_mov_b32 s71, 0x8000
	v_readlane_b32 s62, v251, 27
	v_readlane_b32 s63, v251, 28
	s_waitcnt vmcnt(2)
	v_mul_f32_e32 v7, v1, v6
	s_nop 1
	v_mov_b32_dpp v5, v7 quad_perm:[1,0,3,2] row_mask:0xf bank_mask:0xf bound_ctrl:1
	v_fmac_f32_e32 v5, v1, v6
	s_waitcnt vmcnt(0)
	v_mul_f32_e32 v3, v4, v2
	v_add_f32_dpp v1, v5, v5 quad_perm:[2,3,0,1] row_mask:0xf bank_mask:0xf bound_ctrl:1
	s_nop 1
	v_add_f32_dpp v1, v1, v1 row_half_mirror row_mask:0xf bank_mask:0xf bound_ctrl:1
	s_nop 1
	v_add_f32_dpp v1, v1, v1 row_mirror row_mask:0xf bank_mask:0xf bound_ctrl:1
	v_mov_b32_e32 v5, v1
	s_nop 1
	v_permlane16_swap_b32_e32 v1, v5
	v_add_f32_e32 v196, v1, v5
	s_nop 0
	v_mov_b32_dpp v1, v3 quad_perm:[1,0,3,2] row_mask:0xf bank_mask:0xf bound_ctrl:1
	v_fmac_f32_e32 v1, v4, v2
	v_mov_b32_e32 v5, v97
	v_mov_b32_e32 v197, v196
	v_add_f32_dpp v1, v1, v1 quad_perm:[2,3,0,1] row_mask:0xf bank_mask:0xf bound_ctrl:1
	s_nop 0
	v_permlane32_swap_b32_e32 v196, v197
	v_add_f32_dpp v1, v1, v1 row_half_mirror row_mask:0xf bank_mask:0xf bound_ctrl:1
	s_nop 1
	v_add_f32_dpp v1, v1, v1 row_mirror row_mask:0xf bank_mask:0xf bound_ctrl:1
	v_mov_b32_e32 v2, v1
	s_nop 1
	v_permlane16_swap_b32_e32 v1, v2
	v_add_f32_e32 v198, v1, v2
	v_ashrrev_i32_e32 v1, 31, v0
	v_lshlrev_b64 v[0:1], 10, v[0:1]
	v_lshl_add_u64 v[0:1], s[0:1], 0, v[0:1]
	s_lshl_b32 s0, s37, 7
	s_and_b32 s0, s0, 0x180
	s_lshl_b32 s54, s0, 1
	v_lshl_add_u64 v[182:183], v[0:1], 0, s[54:55]
	v_lshlrev_b32_e32 v0, 6, v195
	v_ashrrev_i32_e32 v1, 31, v0
	v_lshl_add_u64 v[0:1], v[0:1], 1, v[182:183]
	s_movk_i32 s37, 0x100
	v_lshl_add_u64 v[0:1], v[0:1], 0, v[96:97]
	v_cmp_gt_i32_e32 vcc, s37, v200
	global_load_dwordx4 v[110:113], v[0:1], off
	global_load_dwordx4 v[106:109], v[0:1], off offset:32
	global_load_dwordx4 v[102:105], v[0:1], off offset:64
	global_load_dwordx4 v[98:101], v[0:1], off offset:96
	v_cndmask_b32_e64 v0, 12, 8, vcc
	s_movk_i32 s37, 0xe0
	s_lshl_b32 s1, s30, 9
	v_cndmask_b32_e32 v1, v236, v237, vcc
	v_lshlrev_b32_e64 v0, v0, s30
	v_cmp_gt_i32_e32 vcc, s37, v200
	s_or_b32 s0, s0, s1
	v_add3_u32 v0, v1, v200, v0
	v_cndmask_b32_e64 v10, 12, 8, vcc
	s_movk_i32 s37, 0xc0
	s_mul_hi_i32 s1, s0, 0x2200
	s_mulk_i32 s0, 0x2200
	v_ashrrev_i32_e32 v1, 31, v0
	v_cndmask_b32_e32 v11, v236, v237, vcc
	v_lshlrev_b32_e64 v10, v10, s30
	v_cmp_gt_i32_e32 vcc, s37, v200
	s_add_u32 s38, s64, s0
	v_lshlrev_b64 v[0:1], 10, v[0:1]
	v_add3_u32 v10, v11, v14, v10
	v_cndmask_b32_e64 v18, 12, 8, vcc
	s_movk_i32 s37, 0xa0
	s_addc_u32 s39, s65, s1
	v_lshl_add_u64 v[0:1], s[52:53], 0, v[0:1]
	v_lshlrev_b32_e32 v2, 4, v192
	v_ashrrev_i32_e32 v11, 31, v10
	v_cndmask_b32_e32 v19, v236, v237, vcc
	v_lshlrev_b32_e64 v18, v18, s30
	v_cmp_gt_i32_e32 vcc, s37, v200
	v_lshl_add_u64 v[0:1], v[0:1], 0, s[54:55]
	v_and_b32_e32 v4, 0xf0, v2
	v_mov_b64_e32 v[30:31], s[38:39]
	v_lshlrev_b64 v[10:11], 10, v[10:11]
	v_add3_u32 v18, v19, v22, v18
	v_cndmask_b32_e64 v26, 12, 8, vcc
	v_lshl_add_u64 v[0:1], v[0:1], 0, v[4:5]
	v_mad_i64_i32 v[6:7], s[38:39], v200, s41, v[30:31]
	v_lshl_add_u64 v[10:11], s[52:53], 0, v[10:11]
	v_ashrrev_i32_e32 v19, 31, v18
	v_cndmask_b32_e32 v27, v236, v237, vcc
	v_lshlrev_b32_e64 v26, v26, s30
	global_load_dwordx4 v[0:3], v[0:1], off
	v_lshl_add_u64 v[6:7], v[6:7], 0, v[4:5]
	v_lshl_add_u64 v[10:11], v[10:11], 0, s[54:55]
	v_lshlrev_b64 v[18:19], 10, v[18:19]
	v_add3_u32 v26, v27, v32, v26
	global_load_dwordx4 v[6:9], v[6:7], off
	v_lshl_add_u64 v[10:11], v[10:11], 0, v[4:5]
	v_mad_i64_i32 v[14:15], s[38:39], v14, s41, v[30:31]
	v_lshl_add_u64 v[18:19], s[52:53], 0, v[18:19]
	v_ashrrev_i32_e32 v27, 31, v26
	global_load_dwordx4 v[10:13], v[10:11], off
	v_lshl_add_u64 v[14:15], v[14:15], 0, v[4:5]
	v_lshl_add_u64 v[18:19], v[18:19], 0, s[54:55]
	v_lshlrev_b64 v[26:27], 10, v[26:27]
	global_load_dwordx4 v[14:17], v[14:15], off
	v_lshl_add_u64 v[18:19], v[18:19], 0, v[4:5]
	v_mad_i64_i32 v[22:23], s[38:39], v22, s41, v[30:31]
	v_lshl_add_u64 v[26:27], s[52:53], 0, v[26:27]
	global_load_dwordx4 v[18:21], v[18:19], off
	v_lshl_add_u64 v[22:23], v[22:23], 0, v[4:5]
	v_lshl_add_u64 v[26:27], v[26:27], 0, s[54:55]
	global_load_dwordx4 v[22:25], v[22:23], off
	v_lshl_add_u64 v[26:27], v[26:27], 0, v[4:5]
	v_mad_i64_i32 v[30:31], s[38:39], v32, s41, v[30:31]
	global_load_dwordx4 v[26:29], v[26:27], off
	v_lshl_add_u64 v[30:31], v[30:31], 0, v[4:5]
	global_load_dwordx4 v[30:33], v[30:31], off
	s_movk_i32 s37, 0x110
	v_mul_lo_u32 v34, v200, s37
	v_add3_u32 v202, 0, v34, v4
	s_barrier
; DEV int key_of_slot(int x) { return (x & 0x13) | ((x & 8) >> 1) | ((x & 4) << 1); }
; DEV void attn_tile(const Params& p, int l, int tile, char* smem, bool do_store = true) {
;     ...
;   const int nkt = nkeys >> 7;
;   gload(0);
;   __syncthreads();
;   lstore(0);
;   __syncthreads();
;   const int kos = key_of_slot(ql);
	s_waitcnt vmcnt(7)
	ds_write_b128 v202, v[0:3]
	s_waitcnt vmcnt(6)
	ds_write_b128 v202, v[6:9] offset:34816
	s_waitcnt vmcnt(5)
	ds_write_b128 v202, v[10:13] offset:8704
	s_waitcnt vmcnt(4)
	ds_write_b128 v202, v[14:17] offset:43520
	s_waitcnt vmcnt(3)
	ds_write_b128 v202, v[18:21] offset:17408
	s_waitcnt vmcnt(2)
	ds_write_b128 v202, v[22:25] offset:52224
	s_waitcnt vmcnt(1)
	ds_write_b128 v202, v[26:29] offset:26112
	s_waitcnt vmcnt(0)
	ds_write_b128 v202, v[30:33] offset:60928
	v_lshrrev_b32_e32 v1, 1, v192
	v_lshlrev_b32_e32 v2, 1, v192
	v_and_b32_e32 v0, 19, v192
	v_and_b32_e32 v1, 4, v1
	v_and_b32_e32 v2, 8, v2
	v_or3_b32 v0, v1, v0, v2
	v_mul_u32_u24_e32 v203, 0x110, v0
	v_mov_b64_e32 v[0:1], s[0:1]
	v_mad_i64_i32 v[0:1], s[0:1], v200, s41, v[0:1]
	s_add_u32 s38, s52, s54
	v_readlane_b32 s0, v255, 11
	s_addc_u32 s39, s53, 0
	v_or_b32_e32 v0, v0, v4
	v_readlane_b32 s1, v255, 12
	v_mov_b32_e32 v14, v97
	v_mov_b32_e32 v15, v97
	v_mov_b32_e32 v199, v198
	v_lshl_add_u64 v[184:185], s[38:39], 0, v[4:5]
	s_lshl_b32 s36, s36, 7
	v_lshl_add_u64 v[186:187], s[0:1], 0, v[0:1]
	v_mov_b32_e32 v0, v97
	v_mov_b32_e32 v1, v97
	v_mov_b32_e32 v2, v97
	v_mov_b32_e32 v3, v97
	v_mov_b32_e32 v4, v97
	v_mov_b32_e32 v6, v97
	v_mov_b32_e32 v7, v97
	v_mov_b32_e32 v8, v97
	v_mov_b32_e32 v9, v97
	v_mov_b32_e32 v10, v97
	v_mov_b32_e32 v11, v97
	v_mov_b32_e32 v12, v97
	v_mov_b32_e32 v13, v97
	v_mov_b64_e32 v[30:31], v[14:15]
	v_mov_b64_e32 v[46:47], v[14:15]
	v_mov_b64_e32 v[62:63], v[14:15]
	v_permlane32_swap_b32_e32 v198, v199
	s_addk_i32 s36, 0x80
	v_mov_b64_e32 v[28:29], v[12:13]
	v_mov_b64_e32 v[26:27], v[10:11]
	v_mov_b64_e32 v[24:25], v[8:9]
	v_mov_b64_e32 v[22:23], v[6:7]
	v_mov_b64_e32 v[20:21], v[4:5]
	v_mov_b64_e32 v[18:19], v[2:3]
	v_mov_b64_e32 v[16:17], v[0:1]
	v_mov_b64_e32 v[44:45], v[12:13]
	v_mov_b64_e32 v[42:43], v[10:11]
	v_mov_b64_e32 v[40:41], v[8:9]
	v_mov_b64_e32 v[38:39], v[6:7]
	v_mov_b64_e32 v[36:37], v[4:5]
	v_mov_b64_e32 v[34:35], v[2:3]
	v_mov_b64_e32 v[32:33], v[0:1]
	v_mov_b64_e32 v[60:61], v[12:13]
	v_mov_b64_e32 v[58:59], v[10:11]
	v_mov_b64_e32 v[56:57], v[8:9]
	v_mov_b64_e32 v[54:55], v[6:7]
	v_mov_b64_e32 v[52:53], v[4:5]
	v_mov_b64_e32 v[50:51], v[2:3]
	v_mov_b64_e32 v[48:49], v[0:1]
	s_mov_b32 s0, 0
	s_movk_i32 s54, 0x4000
	s_movk_i32 s41, 0x600
	v_readfirstlane_b32 s101, v226
	s_waitcnt lgkmcnt(0)
	s_barrier
	s_lshr_b32 s101, s101, 8
	s_cmp_eq_u32 s101, 0
	s_cbranch_scc1 .Latt_noprio
	s_setprio 1
.Latt_noprio:
	s_branch .LBB0_600
; DEV void attn_tile(const Params& p, int l, int tile, char* smem, bool do_store = true) {
;     ...
;     bf16x8 pb0[2], pb1[2];
;     {
;       float pe[16];
; #pragma unroll
;       for (int e = 0; e < 16; ++e) { pe[e] = __builtin_amdgcn_exp2f(s0[e] - m); lsum += pe[e]; }
; #pragma unroll
;       for (int k2 = 0; k2 < 2; ++k2) {
;         u32x4 u;
;         u[0] = pk2(pe[8 * k2 + 0], pe[8 * k2 + 1]); u[1] = pk2(pe[8 * k2 + 2], pe[8 * k2 + 3]);
;         u[2] = pk2(pe[8 * k2 + 4], pe[8 * k2 + 5]); u[3] = pk2(pe[8 * k2 + 6], pe[8 * k2 + 7]);
;         pb0[k2] = __builtin_bit_cast(bf16x8, u);
;       }
;     }
; #pragma unroll
;     for (int dt = 0; dt < 4; ++dt)
; #pragma unroll
;       for (int k2 = 0; k2 < 2; ++k2) o[dt] = __builtin_amdgcn_mfma_f32_32x32x16_bf16(vf[dt * 2 + k2], pb0[k2], o[dt], 0, 0, 0);
; #pragma unroll
;     for (int dt = 0; dt < 4; ++dt)
; #pragma unroll
;       for (int k2 = 0; k2 < 2; ++k2) vf[dt * 2 + k2] = *(const bf16x8*)(vp + dt * 32 * KROW + (32 + k2 * 16) * 2);
;     {
;       float pe[16];
; #pragma unroll
;       for (int e = 0; e < 16; ++e) { pe[e] = __builtin_amdgcn_exp2f(s1[e] - m); lsum += pe[e]; }
; #pragma unroll
;       for (int k2 = 0; k2 < 2; ++k2) {
;         u32x4 u;
;         u[0] = pk2(pe[8 * k2 + 0], pe[8 * k2 + 1]); u[1] = pk2(pe[8 * k2 + 2], pe[8 * k2 + 3]);
;         u[2] = pk2(pe[8 * k2 + 4], pe[8 * k2 + 5]); u[3] = pk2(pe[8 * k2 + 6], pe[8 * k2 + 7]);
;         pb1[k2] = __builtin_bit_cast(bf16x8, u);
;       }
;     }
; #pragma unroll
;     for (int dt = 0; dt < 4; ++dt)
; #pragma unroll
;       for (int k2 = 0; k2 < 2; ++k2) o[dt] = __builtin_amdgcn_mfma_f32_32x32x16_bf16(vf[dt * 2 + k2], pb1[k2], o[dt], 0, 0, 0);
;     }
;     if (kt + 1 < nkt) lstore(cur ^ 1);
.LBB0_599:
	v_sub_f32_e32 v80, v80, v208
	v_exp_f32_e32 v178, v80
	v_sub_f32_e32 v80, v81, v208
	v_exp_f32_e32 v179, v80
	v_sub_f32_e32 v80, v82, v208
	v_exp_f32_e32 v180, v80
	v_sub_f32_e32 v80, v83, v208
	v_exp_f32_e32 v181, v80
	v_sub_f32_e32 v80, v84, v208
	v_exp_f32_e32 v210, v80
	v_sub_f32_e32 v80, v85, v208
	v_exp_f32_e32 v211, v80
	v_sub_f32_e32 v80, v86, v208
	v_exp_f32_e32 v212, v80
	v_sub_f32_e32 v80, v87, v208
	v_exp_f32_e32 v213, v80
	v_sub_f32_e32 v80, v88, v208
	v_exp_f32_e32 v88, v80
	v_sub_f32_e32 v80, v89, v208
	v_exp_f32_e32 v89, v80
	v_sub_f32_e32 v80, v90, v208
	v_exp_f32_e32 v90, v80
	v_sub_f32_e32 v80, v91, v208
	v_exp_f32_e32 v91, v80
	v_sub_f32_e32 v80, v92, v208
	v_exp_f32_e32 v92, v80
	v_sub_f32_e32 v80, v93, v208
	v_exp_f32_e32 v93, v80
	v_sub_f32_e32 v80, v94, v208
	v_exp_f32_e32 v94, v80
	v_sub_f32_e32 v80, v95, v208
	v_exp_f32_e32 v214, v80
	v_cvt_pk_bf16_f32 v80, v178, v179
	v_cvt_pk_bf16_f32 v81, v180, v181
	v_cvt_pk_bf16_f32 v82, v210, v211
	v_cvt_pk_bf16_f32 v83, v212, v213
	v_add_f32_e32 v95, v178, v209
	v_add_f32_e32 v95, v179, v95
	s_waitcnt lgkmcnt(5)
	v_mfma_f32_32x32x16_bf16 v[32:47], v[166:169], v[80:83], v[32:47]
	v_add_f32_e32 v95, v180, v95
	v_add_f32_e32 v95, v181, v95
	v_add_f32_e32 v95, v210, v95
	v_cvt_pk_bf16_f32 v84, v88, v89
	v_cvt_pk_bf16_f32 v85, v90, v91
	v_cvt_pk_bf16_f32 v86, v92, v93
	v_cvt_pk_bf16_f32 v87, v94, v214
	v_mfma_f32_32x32x16_bf16 v[48:63], v[174:177], v[80:83], v[48:63]
	v_add_f32_e32 v95, v211, v95
	v_sub_f32_e32 v64, v64, v208
	v_add_f32_e32 v95, v212, v95
	v_add_f32_e32 v95, v213, v95
	v_add_f32_e32 v88, v88, v95
	v_add_f32_e32 v88, v89, v88
	v_add_f32_e32 v88, v90, v88
	s_waitcnt lgkmcnt(3)
	v_mfma_f32_32x32x16_bf16 v[16:31], v[146:149], v[80:83], v[16:31]
	v_add_f32_e32 v88, v91, v88
	v_add_f32_e32 v88, v92, v88
	v_add_f32_e32 v88, v93, v88
	v_add_f32_e32 v178, v94, v88
	s_xor_b32 s1, s1, 1
	s_mul_i32 s1, s1, 0x11000
	s_addk_i32 s31, 0x80
	s_waitcnt lgkmcnt(1)
	v_mfma_f32_32x32x16_bf16 v[0:15], v[154:157], v[80:83], v[0:15]
	s_mov_b64 s[38:39], 0x100
	s_add_i32 s0, s0, 1
	v_lshl_add_u64 v[186:187], v[186:187], 0, s[38:39]
	s_cmp_eq_u32 s36, s31
	v_mfma_f32_32x32x16_bf16 v[32:47], v[162:165], v[84:87], v[32:47]
	v_exp_f32_e32 v163, v64
	v_sub_f32_e32 v64, v65, v208
	v_exp_f32_e32 v164, v64
	v_sub_f32_e32 v64, v66, v208
	v_exp_f32_e32 v165, v64
	v_sub_f32_e32 v64, v67, v208
	v_exp_f32_e32 v166, v64
	v_sub_f32_e32 v64, v68, v208
	v_mfma_f32_32x32x16_bf16 v[48:63], v[170:173], v[84:87], v[48:63]
	v_exp_f32_e32 v167, v64
	v_sub_f32_e32 v64, v69, v208
	v_exp_f32_e32 v168, v64
	v_sub_f32_e32 v64, v70, v208
	v_exp_f32_e32 v169, v64
	v_sub_f32_e32 v64, v71, v208
	v_exp_f32_e32 v170, v64
	v_mfma_f32_32x32x16_bf16 v[16:31], v[150:153], v[84:87], v[16:31]
	v_sub_f32_e32 v64, v72, v208
	v_exp_f32_e32 v72, v64
	v_sub_f32_e32 v64, v73, v208
	v_exp_f32_e32 v73, v64
	v_sub_f32_e32 v64, v74, v208
	v_exp_f32_e32 v74, v64
	v_sub_f32_e32 v64, v75, v208
	s_waitcnt lgkmcnt(0)
	v_mfma_f32_32x32x16_bf16 v[0:15], v[158:161], v[84:87], v[0:15]
	ds_read_b128 v[150:153], v205 offset:35008
	ds_read_b128 v[154:157], v205 offset:35040
	ds_read_b128 v[158:161], v205 offset:43712
	ds_read_b128 v[146:149], v205 offset:43744
	ds_read_b128 v[92:95], v205 offset:52416
	ds_read_b128 v[88:91], v205 offset:52448
	ds_read_b128 v[84:87], v205 offset:61120
	ds_read_b128 v[80:83], v205 offset:61152
	v_add_f32_e32 v162, v214, v178
	v_exp_f32_e32 v75, v64
	v_sub_f32_e32 v64, v76, v208
	v_cvt_pk_bf16_f32 v68, v163, v164
	v_cvt_pk_bf16_f32 v69, v165, v166
	v_cvt_pk_bf16_f32 v70, v167, v168
	v_cvt_pk_bf16_f32 v71, v169, v170
	v_exp_f32_e32 v76, v64
	v_sub_f32_e32 v64, v77, v208
	v_add_f32_e32 v162, v163, v162
	s_waitcnt lgkmcnt(7)
	v_mfma_f32_32x32x16_bf16 v[48:63], v[150:153], v[68:71], v[48:63]
	v_add_u32_e32 v206, s1, v202
	s_waitcnt vmcnt(7)
	ds_write_b128 v206, v[114:117]
	s_waitcnt vmcnt(6)
	ds_write_b128 v206, v[118:121] offset:34816
	v_exp_f32_e32 v77, v64
	v_sub_f32_e32 v64, v78, v208
	v_add_f32_e32 v162, v164, v162
	v_exp_f32_e32 v78, v64
	v_sub_f32_e32 v64, v79, v208
	v_add_f32_e32 v162, v165, v162
	v_exp_f32_e32 v79, v64
	s_waitcnt lgkmcnt(7)
	v_mfma_f32_32x32x16_bf16 v[32:47], v[158:161], v[68:71], v[32:47]
	s_waitcnt vmcnt(5)
	ds_write_b128 v206, v[122:125] offset:8704
	s_waitcnt vmcnt(4)
	ds_write_b128 v206, v[126:129] offset:43520
	v_add_f32_e32 v162, v166, v162
	v_add_f32_e32 v162, v167, v162
	v_add_f32_e32 v162, v168, v162
	v_add_f32_e32 v162, v169, v162
	v_cvt_pk_bf16_f32 v64, v72, v73
	v_cvt_pk_bf16_f32 v65, v74, v75
	v_cvt_pk_bf16_f32 v66, v76, v77
	s_waitcnt lgkmcnt(7)
	v_mfma_f32_32x32x16_bf16 v[16:31], v[92:95], v[68:71], v[16:31]
	s_waitcnt vmcnt(3)
	ds_write_b128 v206, v[130:133] offset:17408
	s_waitcnt vmcnt(2)
	ds_write_b128 v206, v[134:137] offset:52224
	v_cvt_pk_bf16_f32 v67, v78, v79
	v_add_f32_e32 v162, v170, v162
	v_add_f32_e32 v72, v72, v162
	v_add_f32_e32 v72, v73, v72
	v_add_f32_e32 v72, v74, v72
	v_add_f32_e32 v72, v75, v72
	v_add_f32_e32 v72, v76, v72
	s_waitcnt lgkmcnt(7)
	v_mfma_f32_32x32x16_bf16 v[0:15], v[84:87], v[68:71], v[0:15]
	s_waitcnt vmcnt(1)
	ds_write_b128 v206, v[138:141] offset:26112
	s_waitcnt vmcnt(0)
	ds_write_b128 v206, v[142:145] offset:60928
	v_add_f32_e32 v72, v77, v72
	v_add_f32_e32 v72, v78, v72
	v_add_f32_e32 v209, v79, v72
	v_mfma_f32_32x32x16_bf16 v[48:63], v[154:157], v[64:67], v[48:63]
	v_mfma_f32_32x32x16_bf16 v[32:47], v[146:149], v[64:67], v[32:47]
	v_mfma_f32_32x32x16_bf16 v[16:31], v[88:91], v[64:67], v[16:31]
	s_waitcnt lgkmcnt(8)
	v_mfma_f32_32x32x16_bf16 v[0:15], v[80:83], v[64:67], v[0:15]
	s_waitcnt lgkmcnt(0)
	s_barrier
	s_cbranch_scc1 .LBB0_604

; DEV void attn_tile(const Params& p, int l, int tile, char* smem, bool do_store = true) {
;     ...
;     bf16x8 pb0[2], pb1[2];
;     {
;       float pe[16];
; #pragma unroll
;       for (int e = 0; e < 16; ++e) { pe[e] = __builtin_amdgcn_exp2f(s0[e] - m); lsum += pe[e]; }
; #pragma unroll
;       for (int k2 = 0; k2 < 2; ++k2) {
;         u32x4 u;
;         u[0] = pk2(pe[8 * k2 + 0], pe[8 * k2 + 1]); u[1] = pk2(pe[8 * k2 + 2], pe[8 * k2 + 3]);
;         u[2] = pk2(pe[8 * k2 + 4], pe[8 * k2 + 5]); u[3] = pk2(pe[8 * k2 + 6], pe[8 * k2 + 7]);
;         pb0[k2] = __builtin_bit_cast(bf16x8, u);
;       }
;     }
; #pragma unroll
;     for (int dt = 0; dt < 4; ++dt)
; #pragma unroll
;       for (int k2 = 0; k2 < 2; ++k2) o[dt] = __builtin_amdgcn_mfma_f32_32x32x16_bf16(vf[dt * 2 + k2], pb0[k2], o[dt], 0, 0, 0);
; #pragma unroll
;     for (int dt = 0; dt < 4; ++dt)
; #pragma unroll
;       for (int k2 = 0; k2 < 2; ++k2) vf[dt * 2 + k2] = *(const bf16x8*)(vp + dt * 32 * KROW + (32 + k2 * 16) * 2);
;     {
;       float pe[16];
; #pragma unroll
;       for (int e = 0; e < 16; ++e) { pe[e] = __builtin_amdgcn_exp2f(s1[e] - m); lsum += pe[e]; }
; #pragma unroll
;       for (int k2 = 0; k2 < 2; ++k2) {
;         u32x4 u;
;         u[0] = pk2(pe[8 * k2 + 0], pe[8 * k2 + 1]); u[1] = pk2(pe[8 * k2 + 2], pe[8 * k2 + 3]);
;         u[2] = pk2(pe[8 * k2 + 4], pe[8 * k2 + 5]); u[3] = pk2(pe[8 * k2 + 6], pe[8 * k2 + 7]);
;         pb1[k2] = __builtin_bit_cast(bf16x8, u);
;       }
;     }
; #pragma unroll
;     for (int dt = 0; dt < 4; ++dt)
; #pragma unroll
;       for (int k2 = 0; k2 < 2; ++k2) o[dt] = __builtin_amdgcn_mfma_f32_32x32x16_bf16(vf[dt * 2 + k2], pb1[k2], o[dt], 0, 0, 0);
;     }
;     if (kt + 1 < nkt) lstore(cur ^ 1);
;     __syncthreads();
;   }
;   const float ltot = xor32_sum(lsum);
;   float* ex = (float*)smem;
;   if (map == 1) {
.LBB0_608:
	v_sub_f32_e32 v80, v80, v131
	v_exp_f32_e32 v132, v80
	v_sub_f32_e32 v80, v81, v131
	v_exp_f32_e32 v133, v80
	v_sub_f32_e32 v80, v82, v131
	v_exp_f32_e32 v134, v80
	v_sub_f32_e32 v80, v83, v131
	v_exp_f32_e32 v135, v80
	v_sub_f32_e32 v80, v84, v131
	v_exp_f32_e32 v136, v80
	v_sub_f32_e32 v80, v85, v131
	v_exp_f32_e32 v137, v80
	v_sub_f32_e32 v80, v86, v131
	v_exp_f32_e32 v138, v80
	v_sub_f32_e32 v80, v87, v131
	v_exp_f32_e32 v139, v80
	v_sub_f32_e32 v80, v88, v131
	v_exp_f32_e32 v140, v80
	v_sub_f32_e32 v80, v89, v131
	v_exp_f32_e32 v141, v80
	v_sub_f32_e32 v80, v90, v131
	v_exp_f32_e32 v142, v80
	v_sub_f32_e32 v80, v91, v131
	v_exp_f32_e32 v143, v80
	v_sub_f32_e32 v80, v92, v131
	v_exp_f32_e32 v144, v80
	v_sub_f32_e32 v80, v93, v131
	v_exp_f32_e32 v145, v80
	v_cvt_pk_bf16_f32 v80, v132, v133
	v_cvt_pk_bf16_f32 v81, v134, v135
	v_cvt_pk_bf16_f32 v82, v136, v137
	v_cvt_pk_bf16_f32 v83, v138, v139
	v_sub_f32_e32 v84, v94, v131
	v_cvt_pk_bf16_f32 v85, v142, v143
	s_waitcnt lgkmcnt(5)
	v_mfma_f32_32x32x16_bf16 v[32:47], v[110:113], v[80:83], v[32:47]
	v_cvt_pk_bf16_f32 v86, v144, v145
	v_sub_f32_e32 v64, v64, v131
	v_cmp_eq_u32_e32 vcc, 1, v195
	v_mfma_f32_32x32x16_bf16 v[48:63], v[126:129], v[80:83], v[48:63]
	v_exp_f32_e32 v126, v84
	v_sub_f32_e32 v84, v95, v131
	v_exp_f32_e32 v127, v84
	v_cvt_pk_bf16_f32 v84, v140, v141
	ds_read_b128 v[88:91], v146 offset:35008
	ds_read_b128 v[92:95], v146 offset:35040
	v_cvt_pk_bf16_f32 v87, v126, v127
	s_waitcnt lgkmcnt(5)
	v_mfma_f32_32x32x16_bf16 v[16:31], v[114:117], v[80:83], v[16:31]
	s_waitcnt lgkmcnt(3)
	v_mfma_f32_32x32x16_bf16 v[0:15], v[102:105], v[80:83], v[0:15]
	v_mfma_f32_32x32x16_bf16 v[32:47], v[106:109], v[84:87], v[32:47]
	v_exp_f32_e32 v106, v64
	v_sub_f32_e32 v64, v65, v131
	v_exp_f32_e32 v107, v64
	v_sub_f32_e32 v64, v66, v131
	v_exp_f32_e32 v108, v64
	v_sub_f32_e32 v64, v67, v131
	v_exp_f32_e32 v102, v64
	v_sub_f32_e32 v64, v68, v131
	v_exp_f32_e32 v103, v64
	v_sub_f32_e32 v64, v69, v131
	v_exp_f32_e32 v104, v64
	v_sub_f32_e32 v64, v70, v131
	v_mfma_f32_32x32x16_bf16 v[48:63], v[122:125], v[84:87], v[48:63]
	v_sub_f32_e32 v68, v78, v131
	v_cvt_pk_bf16_f32 v65, v108, v102
	v_cvt_pk_bf16_f32 v66, v103, v104
	v_mfma_f32_32x32x16_bf16 v[16:31], v[118:121], v[84:87], v[16:31]
	s_waitcnt lgkmcnt(2)
	v_mfma_f32_32x32x16_bf16 v[0:15], v[98:101], v[84:87], v[0:15]
	v_exp_f32_e32 v84, v64
	v_sub_f32_e32 v64, v71, v131
	v_exp_f32_e32 v85, v64
	v_sub_f32_e32 v64, v72, v131
	v_exp_f32_e32 v86, v64
	v_sub_f32_e32 v64, v73, v131
	v_exp_f32_e32 v87, v64
	v_sub_f32_e32 v64, v74, v131
	v_exp_f32_e32 v98, v64
	v_sub_f32_e32 v64, v75, v131
	v_exp_f32_e32 v99, v64
	v_sub_f32_e32 v64, v76, v131
	v_exp_f32_e32 v100, v64
	v_sub_f32_e32 v64, v77, v131
	v_exp_f32_e32 v101, v64
	v_cvt_pk_bf16_f32 v64, v106, v107
	v_cvt_pk_bf16_f32 v67, v84, v85
	v_cvt_pk_bf16_f32 v69, v98, v99
	v_cvt_pk_bf16_f32 v70, v100, v101
	s_waitcnt lgkmcnt(1)
	v_mfma_f32_32x32x16_bf16 v[48:63], v[88:91], v[64:67], v[48:63]
	v_exp_f32_e32 v88, v68
	v_sub_f32_e32 v68, v79, v131
	ds_read_b128 v[72:75], v146 offset:43712
	ds_read_b128 v[76:79], v146 offset:43744
	v_exp_f32_e32 v89, v68
	v_cvt_pk_bf16_f32 v68, v86, v87
	v_cvt_pk_bf16_f32 v71, v88, v89
	s_waitcnt lgkmcnt(1)
	v_mfma_f32_32x32x16_bf16 v[32:47], v[72:75], v[64:67], v[32:47]
	v_add_f32_e32 v72, v132, v130
	v_add_f32_e32 v72, v133, v72
	v_add_f32_e32 v72, v134, v72
	v_add_f32_e32 v72, v135, v72
	v_add_f32_e32 v72, v136, v72
	v_add_f32_e32 v80, v137, v72
	ds_read_b128 v[72:75], v146 offset:52416
	s_waitcnt lgkmcnt(1)
	v_mfma_f32_32x32x16_bf16 v[32:47], v[76:79], v[68:71], v[32:47]
	v_add_f32_e32 v76, v138, v80
	v_add_f32_e32 v76, v139, v76
	v_add_f32_e32 v76, v140, v76
	v_add_f32_e32 v76, v141, v76
	v_add_f32_e32 v76, v142, v76
	v_add_f32_e32 v80, v143, v76
	ds_read_b128 v[76:79], v146 offset:52448
	s_waitcnt lgkmcnt(1)
	v_mfma_f32_32x32x16_bf16 v[16:31], v[72:75], v[64:67], v[16:31]
	v_add_f32_e32 v72, v144, v80
	v_add_f32_e32 v72, v145, v72
	v_add_f32_e32 v90, v126, v72
	ds_read_b128 v[72:75], v146 offset:61120
	ds_read_b128 v[80:83], v146 offset:61152
	v_add_f32_e32 v90, v127, v90
	v_add_f32_e32 v90, v106, v90
	s_waitcnt lgkmcnt(0)
	v_mfma_f32_32x32x16_bf16 v[16:31], v[76:79], v[68:71], v[16:31]
	v_add_f32_e32 v76, v107, v90
	v_add_f32_e32 v76, v108, v76
	v_add_f32_e32 v76, v102, v76
	v_add_f32_e32 v76, v103, v76
	v_add_f32_e32 v76, v104, v76
	v_add_f32_e32 v76, v84, v76
	v_add_f32_e32 v76, v85, v76
	v_mfma_f32_32x32x16_bf16 v[0:15], v[72:75], v[64:67], v[0:15]
	v_add_f32_e32 v64, v86, v76
	v_add_f32_e32 v64, v87, v64
	v_add_f32_e32 v64, v98, v64
	v_add_f32_e32 v64, v99, v64
	v_add_f32_e32 v64, v100, v64
	v_add_f32_e32 v64, v101, v64
	v_add_f32_e32 v64, v88, v64
	v_mfma_f32_32x32x16_bf16 v[48:63], v[92:95], v[68:71], v[48:63]
	v_add_f32_e32 v64, v89, v64
	v_mov_b32_e32 v65, v64
	s_nop 1
	v_permlane32_swap_b32_e32 v64, v65
	v_add_f32_e32 v64, v64, v65
	v_lshlrev_b32_e32 v65, 9, v190
	v_lshlrev_b32_e32 v66, 2, v194
	v_mfma_f32_32x32x16_bf16 v[0:15], v[80:83], v[68:71], v[0:15]
	s_setprio 0
	s_barrier
; DEV void attn_tile(const Params& p, int l, int tile, char* smem, bool do_store = true) {
;     ...
;     lam = __expf(wsum(a1)) - __expf(wsum(a2)) + lam_init;
;     ...
;   if (map == 1) {
;     const float c2 = lam / ltot;
; #pragma unroll
;     for (int dt = 0; dt < 4; ++dt)
; #pragma unroll
;       for (int e = 0; e < 16; ++e) {
;         const int dv = dt * 32 + 8 * (e >> 2) + 4 * hh + (e & 3);
;         ex[(qg * 128 + dv) * 32 + ql] = o[dt][e] * c2;
;       }
;   }
	s_and_saveexec_b64 s[0:1], vcc
	s_cbranch_execz .LBB0_610
	v_add_f32_e32 v67, v196, v197
	v_add_f32_e32 v68, v198, v199
	v_mul_f32_e32 v68, 0x3fb8aa3b, v68
	v_mul_f32_e32 v67, 0x3fb8aa3b, v67
	v_exp_f32_e32 v68, v68
	v_exp_f32_e32 v67, v67
	s_nop 0
	v_sub_f32_e32 v67, v67, v68
	v_add_f32_e32 v67, v188, v67
	v_div_scale_f32 v68, s[30:31], v64, v64, v67
	v_rcp_f32_e32 v69, v68
	v_div_scale_f32 v70, vcc, v67, v64, v67
	v_fma_f32 v71, -v68, v69, 1.0
	v_fmac_f32_e32 v69, v71, v69
	v_mul_f32_e32 v71, v70, v69
	v_fma_f32 v72, -v68, v71, v70
	v_fmac_f32_e32 v71, v72, v69
	v_fma_f32 v68, -v68, v71, v70
	v_div_fmas_f32 v68, v68, v69, v71
	v_div_fixup_f32 v67, v68, v64, v67
	v_lshl_add_u32 v69, v193, 14, 0
	v_mul_f32_e32 v68, v48, v67
	v_add3_u32 v69, v69, v65, v66
	v_mul_f32_e32 v70, v49, v67
	ds_write2_b32 v69, v68, v70 offset1:32
	v_mul_f32_e32 v68, v50, v67
	v_mul_f32_e32 v70, v51, v67
	ds_write2_b32 v69, v68, v70 offset0:64 offset1:96
	v_mul_f32_e32 v68, v52, v67
	v_mul_f32_e32 v70, v53, v67
	v_add_u32_e32 v71, 0x400, v69
	ds_write2_b32 v71, v68, v70 offset1:32
	v_mul_f32_e32 v68, v54, v67
	v_mul_f32_e32 v70, v55, v67
	ds_write2_b32 v71, v68, v70 offset0:64 offset1:96
	v_mul_f32_e32 v68, v56, v67
	v_mul_f32_e32 v70, v57, v67
	v_add_u32_e32 v71, 0x800, v69
	ds_write2_b32 v71, v68, v70 offset1:32
	v_mul_f32_e32 v68, v58, v67
	v_mul_f32_e32 v70, v59, v67
	ds_write2_b32 v71, v68, v70 offset0:64 offset1:96
	v_mul_f32_e32 v68, v60, v67
	v_mul_f32_e32 v70, v61, v67
	v_add_u32_e32 v71, 0xc00, v69
	ds_write2_b32 v71, v68, v70 offset1:32
	v_mul_f32_e32 v68, v62, v67
	v_mul_f32_e32 v70, v63, v67
	ds_write2_b32 v71, v68, v70 offset0:64 offset1:96
	v_mul_f32_e32 v68, v32, v67
	v_mul_f32_e32 v70, v33, v67
	v_add_u32_e32 v71, 0x1000, v69
	ds_write2_b32 v71, v68, v70 offset1:32
	v_mul_f32_e32 v68, v34, v67
	v_mul_f32_e32 v70, v35, v67
	ds_write2_b32 v71, v68, v70 offset0:64 offset1:96
	v_mul_f32_e32 v68, v36, v67
	v_mul_f32_e32 v70, v37, v67
	v_add_u32_e32 v71, 0x1400, v69
	ds_write2_b32 v71, v68, v70 offset1:32
	v_mul_f32_e32 v68, v38, v67
	v_mul_f32_e32 v70, v39, v67
	ds_write2_b32 v71, v68, v70 offset0:64 offset1:96
	v_mul_f32_e32 v68, v40, v67
	v_mul_f32_e32 v70, v41, v67
	v_add_u32_e32 v71, 0x1800, v69
	ds_write2_b32 v71, v68, v70 offset1:32
	v_mul_f32_e32 v68, v42, v67
	v_mul_f32_e32 v70, v43, v67
	ds_write2_b32 v71, v68, v70 offset0:64 offset1:96
	v_mul_f32_e32 v68, v44, v67
	v_mul_f32_e32 v70, v45, v67
	v_add_u32_e32 v71, 0x1c00, v69
	ds_write2_b32 v71, v68, v70 offset1:32
	v_mul_f32_e32 v68, v46, v67
	v_mul_f32_e32 v70, v47, v67
	ds_write2_b32 v71, v68, v70 offset0:64 offset1:96
	v_mul_f32_e32 v68, v16, v67
	v_mul_f32_e32 v70, v17, v67
	v_add_u32_e32 v71, 0x2000, v69
	ds_write2_b32 v71, v68, v70 offset1:32
	v_mul_f32_e32 v68, v18, v67
	v_mul_f32_e32 v70, v19, v67
	ds_write2_b32 v71, v68, v70 offset0:64 offset1:96
	v_mul_f32_e32 v68, v20, v67
	v_mul_f32_e32 v70, v21, v67
	v_add_u32_e32 v71, 0x2400, v69
	ds_write2_b32 v71, v68, v70 offset1:32
	v_mul_f32_e32 v68, v22, v67
	v_mul_f32_e32 v70, v23, v67
	ds_write2_b32 v71, v68, v70 offset0:64 offset1:96
	v_mul_f32_e32 v68, v24, v67
	v_mul_f32_e32 v70, v25, v67
	v_add_u32_e32 v71, 0x2800, v69
	ds_write2_b32 v71, v68, v70 offset1:32
	v_mul_f32_e32 v68, v26, v67
	v_mul_f32_e32 v70, v27, v67
	ds_write2_b32 v71, v68, v70 offset0:64 offset1:96
	v_mul_f32_e32 v68, v28, v67
	v_mul_f32_e32 v70, v29, v67
	v_add_u32_e32 v71, 0x2c00, v69
	ds_write2_b32 v71, v68, v70 offset1:32
	v_mul_f32_e32 v68, v30, v67
	v_mul_f32_e32 v70, v31, v67
	ds_write2_b32 v71, v68, v70 offset0:64 offset1:96
	v_mul_f32_e32 v68, v0, v67
	v_mul_f32_e32 v70, v1, v67
	v_add_u32_e32 v71, 0x3000, v69
	ds_write2_b32 v71, v68, v70 offset1:32
	v_mul_f32_e32 v68, v2, v67
	v_mul_f32_e32 v70, v3, v67
	ds_write2_b32 v71, v68, v70 offset0:64 offset1:96
	v_mul_f32_e32 v68, v4, v67
	v_mul_f32_e32 v70, v5, v67
	v_add_u32_e32 v71, 0x3400, v69
	ds_write2_b32 v71, v68, v70 offset1:32
	v_mul_f32_e32 v68, v6, v67
	v_mul_f32_e32 v70, v7, v67
	ds_write2_b32 v71, v68, v70 offset0:64 offset1:96
	v_mul_f32_e32 v68, v8, v67
	v_mul_f32_e32 v70, v9, v67
	v_add_u32_e32 v71, 0x3800, v69
	ds_write2_b32 v71, v68, v70 offset1:32
	v_mul_f32_e32 v68, v10, v67
	v_mul_f32_e32 v70, v11, v67
	ds_write2_b32 v71, v68, v70 offset0:64 offset1:96
	v_mul_f32_e32 v68, v12, v67
	v_mul_f32_e32 v70, v13, v67
	v_add_u32_e32 v69, 0x3c00, v69
	ds_write2_b32 v69, v68, v70 offset1:32
	v_mul_f32_e32 v68, v14, v67
	v_mul_f32_e32 v67, v15, v67
	ds_write2_b32 v69, v68, v67 offset0:64 offset1:96
